# s5pre kernel-table (kt) accumulation moved from an f32 VALU loop to v_mfma_f32_16x16x4_f32 (exact f32 matrix cores)
# speedup vs baseline: 1.0170x; 1.0129x over previous
; DI void phase_s5pre(LAS unsigned char* lds, PP p, int l, int bid, int nblk) {
;     ...
;         for (int id = tid; id < 32 * 256; id += NTHR) { const int j = id >> 8, ho = (id >> 4) & 15, hi = id & 15; float s = 0.f;
;             for (int pp = 0; pp < 64; ++pp) { const float ar = apr[j * 64 + pp], ai = api[j * 64 + pp], br = bbr[pp * 16 + hi], bi = bbi[pp * 16 + hi];
;                 const float wr_ = ar * br - ai * bi, wi_ = ar * bi + ai * br; s += ccr[ho * 64 + pp] * wr_ - cci[ho * 64 + pp] * wi_; }
;             kt[id] = s; }
.LBB0_255:
	s_or_b64 exec, exec, s[2:3]
	s_waitcnt lgkmcnt(0)
	s_barrier
	s_and_saveexec_b64 s[2:3], s[26:27]
	s_cbranch_execz .LBB0_260
	v_lshrrev_b32_e32 v164, 6, v201
	v_and_b32_e32 v165, 63, v201
	v_lshrrev_b32_e32 v166, 4, v165
	v_and_b32_e32 v167, 15, v165
	v_lshlrev_b32_e32 v168, 10, v164
	v_lshl_add_u32 v168, v166, 2, v168
	v_lshlrev_b32_e32 v169, 8, v167
	v_lshl_add_u32 v169, v166, 2, v169
	v_lshlrev_b32_e32 v170, 6, v166
	v_lshl_add_u32 v170, v167, 2, v170
	v_lshlrev_b32_e32 v171, 12, v164
	v_lshl_add_u32 v171, v166, 8, v171
	v_lshl_add_u32 v171, v167, 2, v171
	ds_read_b32 v60, v169 offset:25088
	ds_read_b32 v61, v169 offset:25104
	ds_read_b32 v62, v169 offset:25120
	ds_read_b32 v63, v169 offset:25136
	ds_read_b32 v64, v169 offset:25152
	ds_read_b32 v65, v169 offset:25168
	ds_read_b32 v66, v169 offset:25184
	ds_read_b32 v67, v169 offset:25200
	s_waitcnt lgkmcnt(0)
	ds_read_b32 v68, v169 offset:25216
	ds_read_b32 v69, v169 offset:25232
	ds_read_b32 v70, v169 offset:25248
	ds_read_b32 v71, v169 offset:25264
	ds_read_b32 v72, v169 offset:25280
	ds_read_b32 v73, v169 offset:25296
	ds_read_b32 v74, v169 offset:25312
	ds_read_b32 v75, v169 offset:25328
	s_waitcnt lgkmcnt(0)
	ds_read_b32 v76, v169 offset:29184
	ds_read_b32 v77, v169 offset:29200
	ds_read_b32 v78, v169 offset:29216
	ds_read_b32 v79, v169 offset:29232
	ds_read_b32 v80, v169 offset:29248
	ds_read_b32 v81, v169 offset:29264
	ds_read_b32 v82, v169 offset:29280
	ds_read_b32 v83, v169 offset:29296
	s_waitcnt lgkmcnt(0)
	ds_read_b32 v84, v169 offset:29312
	ds_read_b32 v85, v169 offset:29328
	ds_read_b32 v86, v169 offset:29344
	ds_read_b32 v87, v169 offset:29360
	ds_read_b32 v88, v169 offset:29376
	ds_read_b32 v89, v169 offset:29392
	ds_read_b32 v90, v169 offset:29408
	ds_read_b32 v91, v169 offset:29424
	s_waitcnt lgkmcnt(0)
	ds_read_b32 v92, v170 offset:16896
	ds_read_b32 v93, v170 offset:17152
	ds_read_b32 v94, v170 offset:17408
	ds_read_b32 v95, v170 offset:17664
	ds_read_b32 v96, v170 offset:17920
	ds_read_b32 v97, v170 offset:18176
	ds_read_b32 v98, v170 offset:18432
	ds_read_b32 v99, v170 offset:18688
	s_waitcnt lgkmcnt(0)
	ds_read_b32 v100, v170 offset:18944
	ds_read_b32 v101, v170 offset:19200
	ds_read_b32 v102, v170 offset:19456
	ds_read_b32 v103, v170 offset:19712
	ds_read_b32 v104, v170 offset:19968
	ds_read_b32 v105, v170 offset:20224
	ds_read_b32 v106, v170 offset:20480
	ds_read_b32 v107, v170 offset:20736
	s_waitcnt lgkmcnt(0)
	ds_read_b32 v108, v170 offset:20992
	ds_read_b32 v109, v170 offset:21248
	ds_read_b32 v110, v170 offset:21504
	ds_read_b32 v111, v170 offset:21760
	ds_read_b32 v112, v170 offset:22016
	ds_read_b32 v113, v170 offset:22272
	ds_read_b32 v114, v170 offset:22528
	ds_read_b32 v115, v170 offset:22784
	s_waitcnt lgkmcnt(0)
	ds_read_b32 v116, v170 offset:23040
	ds_read_b32 v117, v170 offset:23296
	ds_read_b32 v118, v170 offset:23552
	ds_read_b32 v119, v170 offset:23808
	ds_read_b32 v120, v170 offset:24064
	ds_read_b32 v121, v170 offset:24320
	ds_read_b32 v122, v170 offset:24576
	ds_read_b32 v123, v170 offset:24832
	s_waitcnt lgkmcnt(0)
	ds_read_b32 v124, v168 offset:0
	ds_read_b32 v125, v168 offset:8448
	ds_read_b32 v126, v168 offset:256
	ds_read_b32 v127, v168 offset:8704
	ds_read_b32 v128, v168 offset:512
	ds_read_b32 v129, v168 offset:8960
	ds_read_b32 v130, v168 offset:768
	ds_read_b32 v131, v168 offset:9216
	s_waitcnt lgkmcnt(0)
	ds_read_b32 v132, v168 offset:16
	ds_read_b32 v133, v168 offset:8464
	ds_read_b32 v134, v168 offset:272
	ds_read_b32 v135, v168 offset:8720
	ds_read_b32 v136, v168 offset:528
	ds_read_b32 v137, v168 offset:8976
	ds_read_b32 v138, v168 offset:784
	ds_read_b32 v139, v168 offset:9232
	v_mul_f32_e32 v172, v76, v125
	v_fma_f32 v140, v60, v124, -v172
	v_mul_f32_e32 v173, v76, v124
	v_fma_f32 v141, -v60, v125, -v173
	v_mul_f32_e32 v172, v76, v127
	v_fma_f32 v142, v60, v126, -v172
	v_mul_f32_e32 v173, v76, v126
	v_fma_f32 v143, -v60, v127, -v173
	v_mul_f32_e32 v172, v76, v129
	v_fma_f32 v144, v60, v128, -v172
	v_mul_f32_e32 v173, v76, v128
	v_fma_f32 v145, -v60, v129, -v173
	v_mul_f32_e32 v172, v76, v131
	v_fma_f32 v146, v60, v130, -v172
	v_mul_f32_e32 v173, v76, v130
	v_fma_f32 v147, -v60, v131, -v173
	v_mfma_f32_16x16x4_f32 v[148:151], v140, v92, 0
	v_mfma_f32_16x16x4_f32 v[152:155], v142, v92, 0
	v_mfma_f32_16x16x4_f32 v[156:159], v144, v92, 0
	v_mfma_f32_16x16x4_f32 v[160:163], v146, v92, 0
	v_mfma_f32_16x16x4_f32 v[148:151], v141, v108, v[148:151]
	v_mfma_f32_16x16x4_f32 v[152:155], v143, v108, v[152:155]
	v_mfma_f32_16x16x4_f32 v[156:159], v145, v108, v[156:159]
	v_mfma_f32_16x16x4_f32 v[160:163], v147, v108, v[160:163]
	s_waitcnt lgkmcnt(0)
	ds_read_b32 v124, v168 offset:32
	ds_read_b32 v125, v168 offset:8480
	ds_read_b32 v126, v168 offset:288
	ds_read_b32 v127, v168 offset:8736
	ds_read_b32 v128, v168 offset:544
	ds_read_b32 v129, v168 offset:8992
	ds_read_b32 v130, v168 offset:800
	ds_read_b32 v131, v168 offset:9248
	v_mul_f32_e32 v172, v77, v133
	v_fma_f32 v140, v61, v132, -v172
	v_mul_f32_e32 v173, v77, v132
	v_fma_f32 v141, -v61, v133, -v173
	v_mul_f32_e32 v172, v77, v135
	v_fma_f32 v142, v61, v134, -v172
	v_mul_f32_e32 v173, v77, v134
	v_fma_f32 v143, -v61, v135, -v173
	v_mul_f32_e32 v172, v77, v137
	v_fma_f32 v144, v61, v136, -v172
	v_mul_f32_e32 v173, v77, v136
	v_fma_f32 v145, -v61, v137, -v173
	v_mul_f32_e32 v172, v77, v139
	v_fma_f32 v146, v61, v138, -v172
	v_mul_f32_e32 v173, v77, v138
	v_fma_f32 v147, -v61, v139, -v173
	v_mfma_f32_16x16x4_f32 v[148:151], v140, v93, v[148:151]
	v_mfma_f32_16x16x4_f32 v[152:155], v142, v93, v[152:155]
	v_mfma_f32_16x16x4_f32 v[156:159], v144, v93, v[156:159]
	v_mfma_f32_16x16x4_f32 v[160:163], v146, v93, v[160:163]
	v_mfma_f32_16x16x4_f32 v[148:151], v141, v109, v[148:151]
	v_mfma_f32_16x16x4_f32 v[152:155], v143, v109, v[152:155]
	v_mfma_f32_16x16x4_f32 v[156:159], v145, v109, v[156:159]
	v_mfma_f32_16x16x4_f32 v[160:163], v147, v109, v[160:163]
	s_waitcnt lgkmcnt(0)
; DI void phase_s5pre(LAS unsigned char* lds, PP p, int l, int bid, int nblk) {
;     ...
;         for (int id = tid; id < 32 * 256; id += NTHR) { const int j = id >> 8, ho = (id >> 4) & 15, hi = id & 15; float s = 0.f;
;             for (int pp = 0; pp < 64; ++pp) { const float ar = apr[j * 64 + pp], ai = api[j * 64 + pp], br = bbr[pp * 16 + hi], bi = bbi[pp * 16 + hi];
;                 const float wr_ = ar * br - ai * bi, wi_ = ar * bi + ai * br; s += ccr[ho * 64 + pp] * wr_ - cci[ho * 64 + pp] * wi_; }
;             kt[id] = s; }
	ds_read_b32 v132, v168 offset:48
	ds_read_b32 v133, v168 offset:8496
	ds_read_b32 v134, v168 offset:304
	ds_read_b32 v135, v168 offset:8752
	ds_read_b32 v136, v168 offset:560
	ds_read_b32 v137, v168 offset:9008
	ds_read_b32 v138, v168 offset:816
	ds_read_b32 v139, v168 offset:9264
	v_mul_f32_e32 v172, v78, v125
	v_fma_f32 v140, v62, v124, -v172
	v_mul_f32_e32 v173, v78, v124
	v_fma_f32 v141, -v62, v125, -v173
	v_mul_f32_e32 v172, v78, v127
	v_fma_f32 v142, v62, v126, -v172
	v_mul_f32_e32 v173, v78, v126
	v_fma_f32 v143, -v62, v127, -v173
	v_mul_f32_e32 v172, v78, v129
	v_fma_f32 v144, v62, v128, -v172
	v_mul_f32_e32 v173, v78, v128
	v_fma_f32 v145, -v62, v129, -v173
	v_mul_f32_e32 v172, v78, v131
	v_fma_f32 v146, v62, v130, -v172
	v_mul_f32_e32 v173, v78, v130
	v_fma_f32 v147, -v62, v131, -v173
	v_mfma_f32_16x16x4_f32 v[148:151], v140, v94, v[148:151]
	v_mfma_f32_16x16x4_f32 v[152:155], v142, v94, v[152:155]
	v_mfma_f32_16x16x4_f32 v[156:159], v144, v94, v[156:159]
	v_mfma_f32_16x16x4_f32 v[160:163], v146, v94, v[160:163]
	v_mfma_f32_16x16x4_f32 v[148:151], v141, v110, v[148:151]
	v_mfma_f32_16x16x4_f32 v[152:155], v143, v110, v[152:155]
	v_mfma_f32_16x16x4_f32 v[156:159], v145, v110, v[156:159]
	v_mfma_f32_16x16x4_f32 v[160:163], v147, v110, v[160:163]
	s_waitcnt lgkmcnt(0)
	ds_read_b32 v124, v168 offset:64
	ds_read_b32 v125, v168 offset:8512
	ds_read_b32 v126, v168 offset:320
	ds_read_b32 v127, v168 offset:8768
	ds_read_b32 v128, v168 offset:576
	ds_read_b32 v129, v168 offset:9024
	ds_read_b32 v130, v168 offset:832
	ds_read_b32 v131, v168 offset:9280
	v_mul_f32_e32 v172, v79, v133
	v_fma_f32 v140, v63, v132, -v172
	v_mul_f32_e32 v173, v79, v132
	v_fma_f32 v141, -v63, v133, -v173
	v_mul_f32_e32 v172, v79, v135
	v_fma_f32 v142, v63, v134, -v172
	v_mul_f32_e32 v173, v79, v134
	v_fma_f32 v143, -v63, v135, -v173
	v_mul_f32_e32 v172, v79, v137
	v_fma_f32 v144, v63, v136, -v172
	v_mul_f32_e32 v173, v79, v136
	v_fma_f32 v145, -v63, v137, -v173
	v_mul_f32_e32 v172, v79, v139
	v_fma_f32 v146, v63, v138, -v172
	v_mul_f32_e32 v173, v79, v138
	v_fma_f32 v147, -v63, v139, -v173
	v_mfma_f32_16x16x4_f32 v[148:151], v140, v95, v[148:151]
	v_mfma_f32_16x16x4_f32 v[152:155], v142, v95, v[152:155]
	v_mfma_f32_16x16x4_f32 v[156:159], v144, v95, v[156:159]
	v_mfma_f32_16x16x4_f32 v[160:163], v146, v95, v[160:163]
	v_mfma_f32_16x16x4_f32 v[148:151], v141, v111, v[148:151]
	v_mfma_f32_16x16x4_f32 v[152:155], v143, v111, v[152:155]
	v_mfma_f32_16x16x4_f32 v[156:159], v145, v111, v[156:159]
	v_mfma_f32_16x16x4_f32 v[160:163], v147, v111, v[160:163]
	s_waitcnt lgkmcnt(0)
	ds_read_b32 v132, v168 offset:80
	ds_read_b32 v133, v168 offset:8528
	ds_read_b32 v134, v168 offset:336
	ds_read_b32 v135, v168 offset:8784
	ds_read_b32 v136, v168 offset:592
	ds_read_b32 v137, v168 offset:9040
	ds_read_b32 v138, v168 offset:848
	ds_read_b32 v139, v168 offset:9296
	v_mul_f32_e32 v172, v80, v125
	v_fma_f32 v140, v64, v124, -v172
	v_mul_f32_e32 v173, v80, v124
	v_fma_f32 v141, -v64, v125, -v173
	v_mul_f32_e32 v172, v80, v127
	v_fma_f32 v142, v64, v126, -v172
	v_mul_f32_e32 v173, v80, v126
	v_fma_f32 v143, -v64, v127, -v173
	v_mul_f32_e32 v172, v80, v129
	v_fma_f32 v144, v64, v128, -v172
	v_mul_f32_e32 v173, v80, v128
	v_fma_f32 v145, -v64, v129, -v173
	v_mul_f32_e32 v172, v80, v131
	v_fma_f32 v146, v64, v130, -v172
	v_mul_f32_e32 v173, v80, v130
	v_fma_f32 v147, -v64, v131, -v173
	v_mfma_f32_16x16x4_f32 v[148:151], v140, v96, v[148:151]
	v_mfma_f32_16x16x4_f32 v[152:155], v142, v96, v[152:155]
	v_mfma_f32_16x16x4_f32 v[156:159], v144, v96, v[156:159]
	v_mfma_f32_16x16x4_f32 v[160:163], v146, v96, v[160:163]
	v_mfma_f32_16x16x4_f32 v[148:151], v141, v112, v[148:151]
	v_mfma_f32_16x16x4_f32 v[152:155], v143, v112, v[152:155]
	v_mfma_f32_16x16x4_f32 v[156:159], v145, v112, v[156:159]
	v_mfma_f32_16x16x4_f32 v[160:163], v147, v112, v[160:163]
	s_waitcnt lgkmcnt(0)
	ds_read_b32 v124, v168 offset:96
	ds_read_b32 v125, v168 offset:8544
	ds_read_b32 v126, v168 offset:352
	ds_read_b32 v127, v168 offset:8800
	ds_read_b32 v128, v168 offset:608
	ds_read_b32 v129, v168 offset:9056
	ds_read_b32 v130, v168 offset:864
	ds_read_b32 v131, v168 offset:9312
	v_mul_f32_e32 v172, v81, v133
	v_fma_f32 v140, v65, v132, -v172
	v_mul_f32_e32 v173, v81, v132
	v_fma_f32 v141, -v65, v133, -v173
	v_mul_f32_e32 v172, v81, v135
	v_fma_f32 v142, v65, v134, -v172
	v_mul_f32_e32 v173, v81, v134
	v_fma_f32 v143, -v65, v135, -v173
	v_mul_f32_e32 v172, v81, v137
	v_fma_f32 v144, v65, v136, -v172
	v_mul_f32_e32 v173, v81, v136
	v_fma_f32 v145, -v65, v137, -v173
	v_mul_f32_e32 v172, v81, v139
	v_fma_f32 v146, v65, v138, -v172
	v_mul_f32_e32 v173, v81, v138
	v_fma_f32 v147, -v65, v139, -v173
	v_mfma_f32_16x16x4_f32 v[148:151], v140, v97, v[148:151]
	v_mfma_f32_16x16x4_f32 v[152:155], v142, v97, v[152:155]
	v_mfma_f32_16x16x4_f32 v[156:159], v144, v97, v[156:159]
	v_mfma_f32_16x16x4_f32 v[160:163], v146, v97, v[160:163]
	v_mfma_f32_16x16x4_f32 v[148:151], v141, v113, v[148:151]
	v_mfma_f32_16x16x4_f32 v[152:155], v143, v113, v[152:155]
	v_mfma_f32_16x16x4_f32 v[156:159], v145, v113, v[156:159]
	v_mfma_f32_16x16x4_f32 v[160:163], v147, v113, v[160:163]
	s_waitcnt lgkmcnt(0)
; DI void phase_s5pre(LAS unsigned char* lds, PP p, int l, int bid, int nblk) {
;     ...
;         for (int id = tid; id < 32 * 256; id += NTHR) { const int j = id >> 8, ho = (id >> 4) & 15, hi = id & 15; float s = 0.f;
;             for (int pp = 0; pp < 64; ++pp) { const float ar = apr[j * 64 + pp], ai = api[j * 64 + pp], br = bbr[pp * 16 + hi], bi = bbi[pp * 16 + hi];
;                 const float wr_ = ar * br - ai * bi, wi_ = ar * bi + ai * br; s += ccr[ho * 64 + pp] * wr_ - cci[ho * 64 + pp] * wi_; }
;             kt[id] = s; }
	ds_read_b32 v132, v168 offset:112
	ds_read_b32 v133, v168 offset:8560
	ds_read_b32 v134, v168 offset:368
	ds_read_b32 v135, v168 offset:8816
	ds_read_b32 v136, v168 offset:624
	ds_read_b32 v137, v168 offset:9072
	ds_read_b32 v138, v168 offset:880
	ds_read_b32 v139, v168 offset:9328
	v_mul_f32_e32 v172, v82, v125
	v_fma_f32 v140, v66, v124, -v172
	v_mul_f32_e32 v173, v82, v124
	v_fma_f32 v141, -v66, v125, -v173
	v_mul_f32_e32 v172, v82, v127
	v_fma_f32 v142, v66, v126, -v172
	v_mul_f32_e32 v173, v82, v126
	v_fma_f32 v143, -v66, v127, -v173
	v_mul_f32_e32 v172, v82, v129
	v_fma_f32 v144, v66, v128, -v172
	v_mul_f32_e32 v173, v82, v128
	v_fma_f32 v145, -v66, v129, -v173
	v_mul_f32_e32 v172, v82, v131
	v_fma_f32 v146, v66, v130, -v172
	v_mul_f32_e32 v173, v82, v130
	v_fma_f32 v147, -v66, v131, -v173
	v_mfma_f32_16x16x4_f32 v[148:151], v140, v98, v[148:151]
	v_mfma_f32_16x16x4_f32 v[152:155], v142, v98, v[152:155]
	v_mfma_f32_16x16x4_f32 v[156:159], v144, v98, v[156:159]
	v_mfma_f32_16x16x4_f32 v[160:163], v146, v98, v[160:163]
	v_mfma_f32_16x16x4_f32 v[148:151], v141, v114, v[148:151]
	v_mfma_f32_16x16x4_f32 v[152:155], v143, v114, v[152:155]
	v_mfma_f32_16x16x4_f32 v[156:159], v145, v114, v[156:159]
	v_mfma_f32_16x16x4_f32 v[160:163], v147, v114, v[160:163]
	s_waitcnt lgkmcnt(0)
	ds_read_b32 v124, v168 offset:128
	ds_read_b32 v125, v168 offset:8576
	ds_read_b32 v126, v168 offset:384
	ds_read_b32 v127, v168 offset:8832
	ds_read_b32 v128, v168 offset:640
	ds_read_b32 v129, v168 offset:9088
	ds_read_b32 v130, v168 offset:896
	ds_read_b32 v131, v168 offset:9344
	v_mul_f32_e32 v172, v83, v133
	v_fma_f32 v140, v67, v132, -v172
	v_mul_f32_e32 v173, v83, v132
	v_fma_f32 v141, -v67, v133, -v173
	v_mul_f32_e32 v172, v83, v135
	v_fma_f32 v142, v67, v134, -v172
	v_mul_f32_e32 v173, v83, v134
	v_fma_f32 v143, -v67, v135, -v173
	v_mul_f32_e32 v172, v83, v137
	v_fma_f32 v144, v67, v136, -v172
	v_mul_f32_e32 v173, v83, v136
	v_fma_f32 v145, -v67, v137, -v173
	v_mul_f32_e32 v172, v83, v139
	v_fma_f32 v146, v67, v138, -v172
	v_mul_f32_e32 v173, v83, v138
	v_fma_f32 v147, -v67, v139, -v173
	v_mfma_f32_16x16x4_f32 v[148:151], v140, v99, v[148:151]
	v_mfma_f32_16x16x4_f32 v[152:155], v142, v99, v[152:155]
	v_mfma_f32_16x16x4_f32 v[156:159], v144, v99, v[156:159]
	v_mfma_f32_16x16x4_f32 v[160:163], v146, v99, v[160:163]
	v_mfma_f32_16x16x4_f32 v[148:151], v141, v115, v[148:151]
	v_mfma_f32_16x16x4_f32 v[152:155], v143, v115, v[152:155]
	v_mfma_f32_16x16x4_f32 v[156:159], v145, v115, v[156:159]
	v_mfma_f32_16x16x4_f32 v[160:163], v147, v115, v[160:163]
	s_waitcnt lgkmcnt(0)
	ds_read_b32 v132, v168 offset:144
	ds_read_b32 v133, v168 offset:8592
	ds_read_b32 v134, v168 offset:400
	ds_read_b32 v135, v168 offset:8848
	ds_read_b32 v136, v168 offset:656
	ds_read_b32 v137, v168 offset:9104
	ds_read_b32 v138, v168 offset:912
	ds_read_b32 v139, v168 offset:9360
	v_mul_f32_e32 v172, v84, v125
	v_fma_f32 v140, v68, v124, -v172
	v_mul_f32_e32 v173, v84, v124
	v_fma_f32 v141, -v68, v125, -v173
	v_mul_f32_e32 v172, v84, v127
	v_fma_f32 v142, v68, v126, -v172
	v_mul_f32_e32 v173, v84, v126
	v_fma_f32 v143, -v68, v127, -v173
	v_mul_f32_e32 v172, v84, v129
	v_fma_f32 v144, v68, v128, -v172
	v_mul_f32_e32 v173, v84, v128
	v_fma_f32 v145, -v68, v129, -v173
	v_mul_f32_e32 v172, v84, v131
	v_fma_f32 v146, v68, v130, -v172
	v_mul_f32_e32 v173, v84, v130
	v_fma_f32 v147, -v68, v131, -v173
	v_mfma_f32_16x16x4_f32 v[148:151], v140, v100, v[148:151]
	v_mfma_f32_16x16x4_f32 v[152:155], v142, v100, v[152:155]
	v_mfma_f32_16x16x4_f32 v[156:159], v144, v100, v[156:159]
	v_mfma_f32_16x16x4_f32 v[160:163], v146, v100, v[160:163]
	v_mfma_f32_16x16x4_f32 v[148:151], v141, v116, v[148:151]
	v_mfma_f32_16x16x4_f32 v[152:155], v143, v116, v[152:155]
	v_mfma_f32_16x16x4_f32 v[156:159], v145, v116, v[156:159]
	v_mfma_f32_16x16x4_f32 v[160:163], v147, v116, v[160:163]
	s_waitcnt lgkmcnt(0)
	ds_read_b32 v124, v168 offset:160
	ds_read_b32 v125, v168 offset:8608
	ds_read_b32 v126, v168 offset:416
	ds_read_b32 v127, v168 offset:8864
	ds_read_b32 v128, v168 offset:672
	ds_read_b32 v129, v168 offset:9120
	ds_read_b32 v130, v168 offset:928
	ds_read_b32 v131, v168 offset:9376
	v_mul_f32_e32 v172, v85, v133
	v_fma_f32 v140, v69, v132, -v172
	v_mul_f32_e32 v173, v85, v132
	v_fma_f32 v141, -v69, v133, -v173
	v_mul_f32_e32 v172, v85, v135
	v_fma_f32 v142, v69, v134, -v172
	v_mul_f32_e32 v173, v85, v134
	v_fma_f32 v143, -v69, v135, -v173
	v_mul_f32_e32 v172, v85, v137
	v_fma_f32 v144, v69, v136, -v172
	v_mul_f32_e32 v173, v85, v136
	v_fma_f32 v145, -v69, v137, -v173
	v_mul_f32_e32 v172, v85, v139
	v_fma_f32 v146, v69, v138, -v172
	v_mul_f32_e32 v173, v85, v138
	v_fma_f32 v147, -v69, v139, -v173
	v_mfma_f32_16x16x4_f32 v[148:151], v140, v101, v[148:151]
	v_mfma_f32_16x16x4_f32 v[152:155], v142, v101, v[152:155]
	v_mfma_f32_16x16x4_f32 v[156:159], v144, v101, v[156:159]
	v_mfma_f32_16x16x4_f32 v[160:163], v146, v101, v[160:163]
	v_mfma_f32_16x16x4_f32 v[148:151], v141, v117, v[148:151]
	v_mfma_f32_16x16x4_f32 v[152:155], v143, v117, v[152:155]
	v_mfma_f32_16x16x4_f32 v[156:159], v145, v117, v[156:159]
	v_mfma_f32_16x16x4_f32 v[160:163], v147, v117, v[160:163]
	s_waitcnt lgkmcnt(0)
; DI void phase_s5pre(LAS unsigned char* lds, PP p, int l, int bid, int nblk) {
;     ...
;         for (int id = tid; id < 32 * 256; id += NTHR) { const int j = id >> 8, ho = (id >> 4) & 15, hi = id & 15; float s = 0.f;
;             for (int pp = 0; pp < 64; ++pp) { const float ar = apr[j * 64 + pp], ai = api[j * 64 + pp], br = bbr[pp * 16 + hi], bi = bbi[pp * 16 + hi];
;                 const float wr_ = ar * br - ai * bi, wi_ = ar * bi + ai * br; s += ccr[ho * 64 + pp] * wr_ - cci[ho * 64 + pp] * wi_; }
;             kt[id] = s; }
	ds_read_b32 v132, v168 offset:176
	ds_read_b32 v133, v168 offset:8624
	ds_read_b32 v134, v168 offset:432
	ds_read_b32 v135, v168 offset:8880
	ds_read_b32 v136, v168 offset:688
	ds_read_b32 v137, v168 offset:9136
	ds_read_b32 v138, v168 offset:944
	ds_read_b32 v139, v168 offset:9392
	v_mul_f32_e32 v172, v86, v125
	v_fma_f32 v140, v70, v124, -v172
	v_mul_f32_e32 v173, v86, v124
	v_fma_f32 v141, -v70, v125, -v173
	v_mul_f32_e32 v172, v86, v127
	v_fma_f32 v142, v70, v126, -v172
	v_mul_f32_e32 v173, v86, v126
	v_fma_f32 v143, -v70, v127, -v173
	v_mul_f32_e32 v172, v86, v129
	v_fma_f32 v144, v70, v128, -v172
	v_mul_f32_e32 v173, v86, v128
	v_fma_f32 v145, -v70, v129, -v173
	v_mul_f32_e32 v172, v86, v131
	v_fma_f32 v146, v70, v130, -v172
	v_mul_f32_e32 v173, v86, v130
	v_fma_f32 v147, -v70, v131, -v173
	v_mfma_f32_16x16x4_f32 v[148:151], v140, v102, v[148:151]
	v_mfma_f32_16x16x4_f32 v[152:155], v142, v102, v[152:155]
	v_mfma_f32_16x16x4_f32 v[156:159], v144, v102, v[156:159]
	v_mfma_f32_16x16x4_f32 v[160:163], v146, v102, v[160:163]
	v_mfma_f32_16x16x4_f32 v[148:151], v141, v118, v[148:151]
	v_mfma_f32_16x16x4_f32 v[152:155], v143, v118, v[152:155]
	v_mfma_f32_16x16x4_f32 v[156:159], v145, v118, v[156:159]
	v_mfma_f32_16x16x4_f32 v[160:163], v147, v118, v[160:163]
	s_waitcnt lgkmcnt(0)
	ds_read_b32 v124, v168 offset:192
	ds_read_b32 v125, v168 offset:8640
	ds_read_b32 v126, v168 offset:448
	ds_read_b32 v127, v168 offset:8896
	ds_read_b32 v128, v168 offset:704
	ds_read_b32 v129, v168 offset:9152
	ds_read_b32 v130, v168 offset:960
	ds_read_b32 v131, v168 offset:9408
	v_mul_f32_e32 v172, v87, v133
	v_fma_f32 v140, v71, v132, -v172
	v_mul_f32_e32 v173, v87, v132
	v_fma_f32 v141, -v71, v133, -v173
	v_mul_f32_e32 v172, v87, v135
	v_fma_f32 v142, v71, v134, -v172
	v_mul_f32_e32 v173, v87, v134
	v_fma_f32 v143, -v71, v135, -v173
	v_mul_f32_e32 v172, v87, v137
	v_fma_f32 v144, v71, v136, -v172
	v_mul_f32_e32 v173, v87, v136
	v_fma_f32 v145, -v71, v137, -v173
	v_mul_f32_e32 v172, v87, v139
	v_fma_f32 v146, v71, v138, -v172
	v_mul_f32_e32 v173, v87, v138
	v_fma_f32 v147, -v71, v139, -v173
	v_mfma_f32_16x16x4_f32 v[148:151], v140, v103, v[148:151]
	v_mfma_f32_16x16x4_f32 v[152:155], v142, v103, v[152:155]
	v_mfma_f32_16x16x4_f32 v[156:159], v144, v103, v[156:159]
	v_mfma_f32_16x16x4_f32 v[160:163], v146, v103, v[160:163]
	v_mfma_f32_16x16x4_f32 v[148:151], v141, v119, v[148:151]
	v_mfma_f32_16x16x4_f32 v[152:155], v143, v119, v[152:155]
	v_mfma_f32_16x16x4_f32 v[156:159], v145, v119, v[156:159]
	v_mfma_f32_16x16x4_f32 v[160:163], v147, v119, v[160:163]
	s_waitcnt lgkmcnt(0)
	ds_read_b32 v132, v168 offset:208
	ds_read_b32 v133, v168 offset:8656
	ds_read_b32 v134, v168 offset:464
	ds_read_b32 v135, v168 offset:8912
	ds_read_b32 v136, v168 offset:720
	ds_read_b32 v137, v168 offset:9168
	ds_read_b32 v138, v168 offset:976
	ds_read_b32 v139, v168 offset:9424
	v_mul_f32_e32 v172, v88, v125
	v_fma_f32 v140, v72, v124, -v172
	v_mul_f32_e32 v173, v88, v124
	v_fma_f32 v141, -v72, v125, -v173
	v_mul_f32_e32 v172, v88, v127
	v_fma_f32 v142, v72, v126, -v172
	v_mul_f32_e32 v173, v88, v126
	v_fma_f32 v143, -v72, v127, -v173
	v_mul_f32_e32 v172, v88, v129
	v_fma_f32 v144, v72, v128, -v172
	v_mul_f32_e32 v173, v88, v128
	v_fma_f32 v145, -v72, v129, -v173
	v_mul_f32_e32 v172, v88, v131
	v_fma_f32 v146, v72, v130, -v172
	v_mul_f32_e32 v173, v88, v130
	v_fma_f32 v147, -v72, v131, -v173
	v_mfma_f32_16x16x4_f32 v[148:151], v140, v104, v[148:151]
	v_mfma_f32_16x16x4_f32 v[152:155], v142, v104, v[152:155]
	v_mfma_f32_16x16x4_f32 v[156:159], v144, v104, v[156:159]
	v_mfma_f32_16x16x4_f32 v[160:163], v146, v104, v[160:163]
	v_mfma_f32_16x16x4_f32 v[148:151], v141, v120, v[148:151]
	v_mfma_f32_16x16x4_f32 v[152:155], v143, v120, v[152:155]
	v_mfma_f32_16x16x4_f32 v[156:159], v145, v120, v[156:159]
	v_mfma_f32_16x16x4_f32 v[160:163], v147, v120, v[160:163]
	s_waitcnt lgkmcnt(0)
; DI void phase_s5pre(LAS unsigned char* lds, PP p, int l, int bid, int nblk) {
;     ...
;         for (int id = tid; id < 32 * 256; id += NTHR) { const int j = id >> 8, ho = (id >> 4) & 15, hi = id & 15; float s = 0.f;
;             for (int pp = 0; pp < 64; ++pp) { const float ar = apr[j * 64 + pp], ai = api[j * 64 + pp], br = bbr[pp * 16 + hi], bi = bbi[pp * 16 + hi];
;                 const float wr_ = ar * br - ai * bi, wi_ = ar * bi + ai * br; s += ccr[ho * 64 + pp] * wr_ - cci[ho * 64 + pp] * wi_; }
;             kt[id] = s; }
	ds_read_b32 v124, v168 offset:224
	ds_read_b32 v125, v168 offset:8672
	ds_read_b32 v126, v168 offset:480
	ds_read_b32 v127, v168 offset:8928
	ds_read_b32 v128, v168 offset:736
	ds_read_b32 v129, v168 offset:9184
	ds_read_b32 v130, v168 offset:992
	ds_read_b32 v131, v168 offset:9440
	v_mul_f32_e32 v172, v89, v133
	v_fma_f32 v140, v73, v132, -v172
	v_mul_f32_e32 v173, v89, v132
	v_fma_f32 v141, -v73, v133, -v173
	v_mul_f32_e32 v172, v89, v135
	v_fma_f32 v142, v73, v134, -v172
	v_mul_f32_e32 v173, v89, v134
	v_fma_f32 v143, -v73, v135, -v173
	v_mul_f32_e32 v172, v89, v137
	v_fma_f32 v144, v73, v136, -v172
	v_mul_f32_e32 v173, v89, v136
	v_fma_f32 v145, -v73, v137, -v173
	v_mul_f32_e32 v172, v89, v139
	v_fma_f32 v146, v73, v138, -v172
	v_mul_f32_e32 v173, v89, v138
	v_fma_f32 v147, -v73, v139, -v173
	v_mfma_f32_16x16x4_f32 v[148:151], v140, v105, v[148:151]
	v_mfma_f32_16x16x4_f32 v[152:155], v142, v105, v[152:155]
	v_mfma_f32_16x16x4_f32 v[156:159], v144, v105, v[156:159]
	v_mfma_f32_16x16x4_f32 v[160:163], v146, v105, v[160:163]
	v_mfma_f32_16x16x4_f32 v[148:151], v141, v121, v[148:151]
	v_mfma_f32_16x16x4_f32 v[152:155], v143, v121, v[152:155]
	v_mfma_f32_16x16x4_f32 v[156:159], v145, v121, v[156:159]
	v_mfma_f32_16x16x4_f32 v[160:163], v147, v121, v[160:163]
	s_waitcnt lgkmcnt(0)
	ds_read_b32 v132, v168 offset:240
	ds_read_b32 v133, v168 offset:8688
	ds_read_b32 v134, v168 offset:496
	ds_read_b32 v135, v168 offset:8944
	ds_read_b32 v136, v168 offset:752
	ds_read_b32 v137, v168 offset:9200
	ds_read_b32 v138, v168 offset:1008
	ds_read_b32 v139, v168 offset:9456
	v_mul_f32_e32 v172, v90, v125
	v_fma_f32 v140, v74, v124, -v172
	v_mul_f32_e32 v173, v90, v124
	v_fma_f32 v141, -v74, v125, -v173
	v_mul_f32_e32 v172, v90, v127
	v_fma_f32 v142, v74, v126, -v172
	v_mul_f32_e32 v173, v90, v126
	v_fma_f32 v143, -v74, v127, -v173
	v_mul_f32_e32 v172, v90, v129
	v_fma_f32 v144, v74, v128, -v172
	v_mul_f32_e32 v173, v90, v128
	v_fma_f32 v145, -v74, v129, -v173
	v_mul_f32_e32 v172, v90, v131
	v_fma_f32 v146, v74, v130, -v172
	v_mul_f32_e32 v173, v90, v130
	v_fma_f32 v147, -v74, v131, -v173
	v_mfma_f32_16x16x4_f32 v[148:151], v140, v106, v[148:151]
	v_mfma_f32_16x16x4_f32 v[152:155], v142, v106, v[152:155]
	v_mfma_f32_16x16x4_f32 v[156:159], v144, v106, v[156:159]
	v_mfma_f32_16x16x4_f32 v[160:163], v146, v106, v[160:163]
	v_mfma_f32_16x16x4_f32 v[148:151], v141, v122, v[148:151]
	v_mfma_f32_16x16x4_f32 v[152:155], v143, v122, v[152:155]
	v_mfma_f32_16x16x4_f32 v[156:159], v145, v122, v[156:159]
	v_mfma_f32_16x16x4_f32 v[160:163], v147, v122, v[160:163]
	s_waitcnt lgkmcnt(0)
	v_mul_f32_e32 v172, v91, v133
	v_fma_f32 v140, v75, v132, -v172
	v_mul_f32_e32 v173, v91, v132
	v_fma_f32 v141, -v75, v133, -v173
	v_mul_f32_e32 v172, v91, v135
	v_fma_f32 v142, v75, v134, -v172
	v_mul_f32_e32 v173, v91, v134
	v_fma_f32 v143, -v75, v135, -v173
	v_mul_f32_e32 v172, v91, v137
	v_fma_f32 v144, v75, v136, -v172
	v_mul_f32_e32 v173, v91, v136
	v_fma_f32 v145, -v75, v137, -v173
	v_mul_f32_e32 v172, v91, v139
	v_fma_f32 v146, v75, v138, -v172
	v_mul_f32_e32 v173, v91, v138
	v_fma_f32 v147, -v75, v139, -v173
	v_mfma_f32_16x16x4_f32 v[148:151], v140, v107, v[148:151]
	v_mfma_f32_16x16x4_f32 v[152:155], v142, v107, v[152:155]
	v_mfma_f32_16x16x4_f32 v[156:159], v144, v107, v[156:159]
	v_mfma_f32_16x16x4_f32 v[160:163], v146, v107, v[160:163]
	v_mfma_f32_16x16x4_f32 v[148:151], v141, v123, v[148:151]
	v_mfma_f32_16x16x4_f32 v[152:155], v143, v123, v[152:155]
	v_mfma_f32_16x16x4_f32 v[156:159], v145, v123, v[156:159]
	v_mfma_f32_16x16x4_f32 v[160:163], v147, v123, v[160:163]
	s_nop 7
	s_nop 2
	ds_write_b32 v171, v148 offset:33280
	ds_write_b32 v171, v149 offset:33344
	ds_write_b32 v171, v150 offset:33408
	ds_write_b32 v171, v151 offset:33472
	ds_write_b32 v171, v152 offset:34304
	ds_write_b32 v171, v153 offset:34368
	ds_write_b32 v171, v154 offset:34432
	ds_write_b32 v171, v155 offset:34496
	ds_write_b32 v171, v156 offset:35328
	ds_write_b32 v171, v157 offset:35392
	ds_write_b32 v171, v158 offset:35456
	ds_write_b32 v171, v159 offset:35520
	ds_write_b32 v171, v160 offset:36352
	ds_write_b32 v171, v161 offset:36416
	ds_write_b32 v171, v162 offset:36480
	ds_write_b32 v171, v163 offset:36544
